# NSA compressed phase: workgroups >= 256 take the mirrored query-block index so CU-mates pair a heavy unit with a light one
# speedup vs baseline: 1.0098x; 1.0098x over previous
; DI void gemm_phase(const Params& p, const GemmJob& j, int nmt, int ntn, char* smem) {
;   const int xcd = blockIdx.x & 7, jl = blockIdx.x >> 3, nloc = (gridDim.x + 7 - xcd) >> 3;
;   const int ngroups = nmt >> 2; const int ngx = (ngroups - xcd + 7) >> 3;
;   const int per = 4 * ntn, entries = ngx * per;
; __global__ void __launch_bounds__(256, 2) mega_kernel(Params p) {
;     ...
;       for (int u = blockIdx.x; u < 512; u += G) nsa_cmp_unit(p, u, smem);
;     ...
;       for (int u = blockIdx.x; u < 512; u += G) nsa_cmp_unit(p, u, smem);
;       if (G == 512) {
;         const int qb = blockIdx.x & 31, grp = blockIdx.x >> 5;
;         int c0 = 0;
;         for (int q = 0; q < qb; ++q) c0 += ((31 - q) * 8 + 15) / 31;
;         const int n = ((31 - qb) * 8 + 15) / 31;
;         for (int k = 0; k < n; ++k) nsa_win_unit(p, 2048 + grp * 128 + c0 + k, smem);
.LBB0_79:
	s_or_b64 exec, exec, s[4:5]
	s_add_i32 s0, s82, -1
	s_cmp_eq_u32 s86, s0
	s_cselect_b64 s[74:75], -1, 0
	s_load_dwordx16 s[12:27], s[80:81], 0xd0
	s_and_b32 s2, s86, 7
	s_xor_b32 s0, s2, 7
	s_add_i32 s0, s82, s0
	s_lshr_b32 s71, s0, 3
	s_lshl_b32 s0, s2, 2
	s_lshr_b32 s90, s86, 3
	v_writelane_b32 v230, s0, 4
	s_lshl_b32 s0, s2, 8
	s_waitcnt lgkmcnt(0)
	s_add_u32 s96, s16, s0
	s_addc_u32 s97, s17, 0
	s_min_u32 s0, s82, 8
	v_writelane_b32 v230, s0, 5
	s_add_u32 s0, s16, 0x1000
	s_addc_u32 s1, s17, 0
	s_load_dwordx16 s[36:51], s[80:81], 0x110
	v_writelane_b32 v230, s0, 6
	s_cmpk_lt_i32 s86, 0x1000
	s_mov_b32 s59, 0
	v_writelane_b32 v230, s1, 7
	s_cselect_b64 s[0:1], -1, 0
	s_lshl_b32 s91, s82, 1
	v_writelane_b32 v230, s0, 8
	s_cmpk_lt_i32 s86, 0x3000
	s_mov_b32 s83, s59
	v_writelane_b32 v230, s1, 9
	s_cselect_b64 s[0:1], -1, 0
	v_writelane_b32 v230, s0, 10
	s_lshl_b64 s[8:9], s[82:83], 8
	v_lshrrev_b32_e32 v169, 3, v167
	v_writelane_b32 v230, s1, 11
	s_waitcnt lgkmcnt(0)
	s_add_u32 s0, s40, 0x200000
	s_addc_u32 s1, s41, 0
	v_writelane_b32 v230, s0, 12
	v_mov_b32_e32 v1, 0
	v_and_b32_e32 v174, 4, v169
	v_writelane_b32 v230, s1, 13
	s_add_u32 s0, s40, 0x400000
	s_addc_u32 s1, s41, 0
	s_add_u32 s10, s24, 0x4000000
	v_writelane_b32 v230, s0, 14
	s_addc_u32 s11, s25, 0
	v_add_u32_e32 v171, 32, v169
	v_writelane_b32 v230, s1, 15
	s_add_u32 s0, s24, 0x8000000
	s_addc_u32 s1, s25, 0
	v_writelane_b32 v230, s0, 16
	s_cmpk_eq_i32 s82, 0x200
	v_lshlrev_b32_e32 v170, 12, v169
	v_writelane_b32 v230, s1, 17
	s_cselect_b64 s[0:1], -1, 0
	s_cmpk_lg_i32 s82, 0x200
	v_writelane_b32 v230, s0, 18
	s_cselect_b64 s[30:31], -1, 0
	s_cmpk_lt_i32 s86, 0x800
	v_writelane_b32 v230, s1, 19
	s_cselect_b64 s[0:1], -1, 0
	v_writelane_b32 v230, s0, 20
	v_lshlrev_b32_e32 v176, 12, v171
	v_mov_b32_e32 v201, 0x358637bd
	v_writelane_b32 v230, s1, 21
	s_add_u32 s0, s26, 0x1800000
	v_writelane_b32 v230, s0, 22
	s_addc_u32 s0, s27, 0
	v_writelane_b32 v230, s0, 23
	s_add_u32 s0, s36, 0x800000
	v_writelane_b32 v230, s0, 24
	s_addc_u32 s0, s37, 0
	v_writelane_b32 v230, s0, 25
	v_sub_co_u32_e64 v2, s[0:1], s86, 64
	s_xor_b64 s[0:1], s[0:1], -1
	s_cmp_lt_i32 s86, 32
	s_cselect_b64 s[4:5], -1, 0
	s_add_i32 s3, s86, 0x800
	v_writelane_b32 v230, s4, 26
	s_cmpk_lt_i32 s3, 0x1000
	v_mov_b32_e32 v203, 0x41b17218
	v_writelane_b32 v230, s5, 27
	s_cselect_b64 s[4:5], -1, 0
	s_cmpk_lt_i32 s86, 0x200
	s_cselect_b64 s[34:35], -1, 0
	s_and_b32 s69, s86, 31
	s_cmpk_lg_u32 s82, 0x200
	s_cbranch_scc1 .Lqbflip_skip
	s_cmpk_lt_u32 s86, 0x100
	s_cbranch_scc1 .Lqbflip_skip
	s_xor_b32 s69, s69, 31
; __global__ void __launch_bounds__(256, 2) mega_kernel(Params p) {
;     ...
;       for (int u = blockIdx.x; u < 512; u += G) nsa_cmp_unit(p, u, smem);
;       if (G == 512) {
;         const int qb = blockIdx.x & 31, grp = blockIdx.x >> 5;
;         int c0 = 0;
;         for (int q = 0; q < qb; ++q) c0 += ((31 - q) * 8 + 15) / 31;
;         const int n = ((31 - qb) * 8 + 15) / 31;
;         for (int k = 0; k < n; ++k) nsa_win_unit(p, 2048 + grp * 128 + c0 + k, smem);
;       }
.Lqbflip_skip:
	v_writelane_b32 v230, s3, 28
	s_lshl_b32 s3, s69, 3
	s_xor_b32 s3, s3, 0xf8
	s_mul_i32 s6, s3, 0x843
	s_addk_i32 s6, 0x7bed
	v_writelane_b32 v230, s34, 29
	s_lshr_b32 s6, s6, 16
	s_cmp_gt_u32 s3, 15
	v_writelane_b32 v230, s35, 30
	v_writelane_b32 v230, s6, 31
	s_cselect_b64 s[34:35], -1, 0
	v_writelane_b32 v230, s34, 32
	s_and_b32 s3, s28, 0x7fffff80
	s_addk_i32 s3, 0x800
	v_writelane_b32 v230, s35, 33
	v_writelane_b32 v230, s28, 34
	v_writelane_b32 v230, s3, 35
	s_add_u32 s3, s26, 0x1000000
	v_writelane_b32 v230, s3, 36
	s_addc_u32 s3, s27, 0
	s_cmpk_lt_u32 s86, 0x400
	v_writelane_b32 v230, s3, 37
	s_cselect_b64 s[28:29], -1, 0
	s_lshl_b32 s70, s2, 10
	s_movk_i32 s2, 0x800
	v_writelane_b32 v230, s28, 38
	s_cmp_eq_u64 s[18:19], 0
	v_cmp_gt_i32_e32 vcc, s2, v2
	v_writelane_b32 v230, s29, 39
	s_cselect_b64 s[2:3], -1, 0
	s_and_b64 s[0:1], s[0:1], vcc
	v_writelane_b32 v230, s0, 40
	v_mov_b32_e32 v204, 0xff800000
	v_not_b32_e32 v205, 32
	v_writelane_b32 v230, s1, 41
	v_writelane_b32 v230, s30, 42
	s_and_b64 s[0:1], s[30:31], s[4:5]
	s_load_dwordx2 s[4:5], s[80:81], 0x0
	v_writelane_b32 v230, s31, 43
	v_writelane_b32 v230, s0, 44
	v_mbcnt_hi_u32_b32 v202, -1, v10
	v_mov_b32_e32 v206, 0xf149f2ca
	v_writelane_b32 v230, s1, 45
	s_and_b32 s0, s69, 30
	s_cmp_lg_u32 s69, s0
	v_writelane_b32 v230, s0, 46
	s_cselect_b64 s[0:1], -1, 0
	v_writelane_b32 v230, s0, 47
	v_mov_b32_e32 v207, 0x3f80
	v_mov_b32_e32 v208, 0x3f00
	v_writelane_b32 v230, s1, 48
	s_abs_i32 s0, s82
	v_cvt_f32_u32_e32 v0, s0
	v_writelane_b32 v230, s0, 49
	s_sub_i32 s0, 0, s0
	s_mov_b32 s34, 0x3fb8aa3b
	v_rcp_iflag_f32_e32 v0, v0
	s_mov_b32 s35, 0xff800000
	s_mov_b32 s60, 0xf0c9f2ca
	s_mov_b32 s61, 0x5040100
	v_mul_f32_e32 v0, 0x4f7ffffe, v0
	v_cvt_u32_f32_e32 v0, v0
	s_mov_b64 s[88:89], 0x200000
	s_mov_b64 s[92:93], 0x400000
	s_mov_b64 s[84:85], 0x402000
	v_readfirstlane_b32 s1, v0
	s_mul_i32 s0, s0, s1
	s_mul_hi_u32 s0, s1, s0
	s_add_i32 s0, s1, s0
	v_writelane_b32 v230, s0, 50
	v_writelane_b32 v230, s36, 51
	s_ashr_i32 s0, s82, 31
	v_lshrrev_b32_e32 v0, 2, v167
	v_writelane_b32 v229, s49, 0
	v_writelane_b32 v229, s50, 1
	v_writelane_b32 v229, s51, 2
	v_writelane_b32 v229, s10, 3
	v_writelane_b32 v230, s37, 52
	v_writelane_b32 v230, s38, 53
	v_writelane_b32 v229, s11, 4
	v_writelane_b32 v229, s0, 5
	s_lshl_b32 s0, s90, 5
	v_writelane_b32 v229, s0, 6
	s_lshl_b32 s0, s71, 5
	v_writelane_b32 v229, s0, 7
	s_add_u32 s0, s22, 0x400000
	s_addc_u32 s1, s23, 0
	v_writelane_b32 v229, s0, 8
	s_add_u32 s77, s80, 0x160
	s_addc_u32 s76, s81, 0
	v_writelane_b32 v229, s1, 9
	v_readfirstlane_b32 s0, v2
	s_mov_b32 s1, 0
	s_xor_b64 s[72:73], s[2:3], -1
	v_writelane_b32 v229, s0, 10
	s_lshl_b32 s0, s86, 7
	v_writelane_b32 v229, s0, 11
	s_lshl_b32 s0, s82, 7
	v_writelane_b32 v229, s0, 12
	s_lshl_b32 s0, s86, 8
	v_writelane_b32 v229, s0, 13
	s_lshl_b32 s0, s82, 8
	v_writelane_b32 v229, s0, 14
	s_add_i32 s0, 0, 0xd000
	v_writelane_b32 v229, s0, 15
	v_writelane_b32 v229, s1, 16
	v_cmp_eq_u32_e64 s[2:3], 0, v167
	v_writelane_b32 v230, s39, 54
	v_writelane_b32 v230, s40, 55
	v_writelane_b32 v229, s2, 17
	v_writelane_b32 v230, s41, 56
	v_writelane_b32 v230, s42, 57
	v_writelane_b32 v229, s3, 18
	s_load_dwordx2 s[2:3], s[80:81], 0x150
	v_writelane_b32 v230, s43, 58
	v_writelane_b32 v230, s44, 59
	v_and_b32_e32 v166, 8, v0
	v_lshlrev_b32_e32 v0, 3, v167
	s_waitcnt lgkmcnt(0)
	v_writelane_b32 v229, s2, 19
	v_writelane_b32 v230, s45, 60
	v_and_b32_e32 v168, 56, v0
	v_writelane_b32 v229, s3, 20
	s_lshl_b64 s[2:3], s[86:87], 11
	v_writelane_b32 v229, s2, 21
	v_lshlrev_b32_e32 v0, 13, v169
	v_writelane_b32 v230, s46, 61
	v_writelane_b32 v229, s3, 22
	v_writelane_b32 v229, s4, 23
	v_writelane_b32 v230, s47, 62
	v_lshl_add_u64 v[172:173], s[36:37], 0, v[0:1]
	v_writelane_b32 v229, s5, 24
	s_load_dwordx4 s[4:7], s[80:81], 0x30
	v_mul_u32_u24_e32 v0, 0x48, v169
	v_writelane_b32 v230, s48, 63
	s_mov_b64 s[48:49], s[8:9]
	v_lshlrev_b32_e32 v0, 1, v0
	s_waitcnt lgkmcnt(0)
	v_writelane_b32 v229, s4, 25
	v_lshlrev_b32_e32 v3, 1, v168
	v_add3_u32 v175, 0, v0, v3
	v_writelane_b32 v229, s5, 26
	v_writelane_b32 v229, s6, 27
	v_writelane_b32 v229, s7, 28
	v_writelane_b32 v229, s12, 29
	v_and_b32_e32 v0, 31, v167
	v_bfe_u32 v3, v167, 5, 1
	v_writelane_b32 v229, s13, 30
	v_writelane_b32 v229, s14, 31
	v_writelane_b32 v229, s15, 32
	v_writelane_b32 v229, s16, 33
	v_writelane_b32 v229, s17, 34
	v_writelane_b32 v229, s18, 35
	v_writelane_b32 v229, s19, 36
	v_writelane_b32 v229, s20, 37
	v_writelane_b32 v229, s21, 38
	v_writelane_b32 v229, s22, 39
	v_writelane_b32 v229, s23, 40
	v_writelane_b32 v229, s24, 41
	v_writelane_b32 v229, s25, 42
	v_writelane_b32 v229, s26, 43
	v_writelane_b32 v229, s27, 44
	v_writelane_b32 v229, s69, 45
	v_writelane_b32 v229, s70, 46
	v_writelane_b32 v229, s72, 47
	v_mul_u32_u24_e32 v0, 0x48, v0
	s_lshl_b64 s[2:3], s[82:83], 11
	v_writelane_b32 v229, s73, 48
	v_writelane_b32 v229, s96, 49
	v_lshlrev_b32_e32 v4, 3, v3
	v_lshl_add_u32 v177, v3, 4, 0
	v_writelane_b32 v229, s97, 50
	v_writelane_b32 v229, s48, 51
	v_lshlrev_b32_e32 v0, 1, v0
	v_add_u32_e32 v196, v177, v0
	v_writelane_b32 v229, s49, 52
	v_writelane_b32 v229, s2, 53
	v_add3_u32 v198, 0, v0, v4
	v_lshlrev_b32_e32 v0, 1, v174
	v_writelane_b32 v229, s3, 54
	v_lshlrev_b32_e32 v197, 2, v3
	v_add_u32_e32 v199, v198, v4
	v_sub_u32_e32 v200, 0, v4
	v_lshl_add_u64 v[178:179], s[10:11], 0, v[0:1]
	s_movk_i32 s0, 0x110
	s_mov_b64 s[52:53], 0x403000
	s_mov_b64 s[56:57], 0x10000
	s_mov_b32 s50, s59
	v_writelane_b32 v229, s74, 55
	s_barrier
	s_nop 0
	v_writelane_b32 v229, s75, 56
	s_branch .LBB0_82

; DI void nsa_cmp_unit(const Params& p, int u, char* smem) {
;     ...
;   __syncthreads();
; __global__ void __launch_bounds__(256, 2) mega_kernel(Params p) {
;     ...
;       for (int u = blockIdx.x; u < 512; u += G) nsa_cmp_unit(p, u, smem);
.LBB0_371:
	s_or_b64 exec, exec, s[2:3]
	v_readlane_b32 s2, v230, 29
	v_readlane_b32 s3, v230, 30
	s_andn2_b64 vcc, exec, s[2:3]
	v_readlane_b32 s1, v229, 45
	s_andn2_b32 s100, s86, 31
	s_nop 1
	s_or_b32 s1, s1, s100
	s_barrier
	s_cbranch_vccz .LBB0_430
